# conv arithmetic done in alpha A straight from the stage registers (16 copies removed); beta A only stores the packed row
# baseline (speedup 1.0000x reference)
.Lev_skip_a:
	s_add_i32 s34, s49, 3
	v_sub_u32_e64 v32, 60, s44 clamp
	s_and_b64 s[20:21], exec, s[38:39]
	v_readfirstlane_b32 s20, v32
	s_cselect_b32 s66, s34, s20
	s_lshl_b32 s34, s66, 13
	s_lshl_b32 s67, s66, 14
	s_add_u32 s20, s43, s67
	s_addc_u32 s21, s63, 0
	v_lshl_add_u64 v[36:37], s[20:21], 0, v[120:121]
	global_load_dwordx4 v[32:35], v120, s[20:21] nt
	v_add_co_u32_e64 v36, s[20:21], s60, v36
	v_lshl_add_u64 v[48:49], v[146:147], 0, s[34:35]
	global_load_dwordx4 v[48:51], v[48:49], off nt
	s_nop 0
	v_addc_co_u32_e64 v37, s[20:21], 0, v37, s[20:21]
	s_add_u32 s20, s64, s67
	s_addc_u32 s21, s65, 0
	v_lshl_add_u64 v[44:45], s[20:21], 0, v[120:121]
	global_load_dwordx4 v[36:39], v[36:37], off nt
	s_lshl_b32 s34, s66, 10
	global_load_dwordx4 v[40:43], v120, s[20:21] nt
	v_add_co_u32_e64 v44, s[20:21], s60, v44
	v_lshl_add_u64 v[52:53], v[148:149], 0, s[34:35]
	global_load_dwordx4 v[52:55], v[52:53], off
	s_nop 0
	v_addc_co_u32_e64 v45, s[20:21], 0, v45, s[20:21]
	global_load_dwordx4 v[44:47], v[44:45], off nt
	s_lshl_b32 s20, s49, 1
	s_add_i32 s34, s20, 4
	s_waitcnt vmcnt(16)
	s_waitcnt vmcnt(15)
	v_and_b32_e32 v250, 0xfff, v184
	v_cmp_ne_u32_e64 s[20:21], 0, v250
	v_add_u32_e32 v184, 4, v184
	s_nop 0
	v_cndmask_b32_e64 v56, 0, v56, s[20:21]
	v_cndmask_b32_e64 v57, 0, v57, s[20:21]
	v_cndmask_b32_e64 v58, 0, v58, s[20:21]
	v_cndmask_b32_e64 v59, 0, v59, s[20:21]
	v_cmp_ne_u32_e64 s[20:21], s62, v250
	v_lshlrev_b32_e32 v246, 16, v60
	v_and_b32_e32 v247, 0xffff0000, v60
	v_cndmask_b32_e64 v64, 0, v64, s[20:21]
	v_cndmask_b32_e64 v65, 0, v65, s[20:21]
	v_cndmask_b32_e64 v66, 0, v66, s[20:21]
	v_cndmask_b32_e64 v67, 0, v67, s[20:21]
	v_pk_mul_f32 v[246:247], v[8:9], v[246:247]
	v_lshlrev_b32_e32 v248, 16, v56
	v_and_b32_e32 v249, 0xffff0000, v56
	v_pk_fma_f32 v[246:247], v[0:1], v[248:249], v[246:247]
	v_lshlrev_b32_e32 v248, 16, v64
	v_and_b32_e32 v249, 0xffff0000, v64
	v_pk_fma_f32 v[246:247], v[16:17], v[248:249], v[246:247]
	v_pk_add_f32 v[246:247], v[24:25], v[246:247]
	v_lshlrev_b32_e32 v248, 16, v68
	v_and_b32_e32 v249, 0xffff0000, v68
	v_pk_mul_f32 v[246:247], v[246:247], v[248:249]
	v_cvt_pk_bf16_f32 v198, v246, v247
	v_lshlrev_b32_e32 v246, 16, v61
	v_and_b32_e32 v247, 0xffff0000, v61
	v_pk_mul_f32 v[246:247], v[10:11], v[246:247]
	v_lshlrev_b32_e32 v248, 16, v57
	v_and_b32_e32 v249, 0xffff0000, v57
	v_pk_fma_f32 v[246:247], v[2:3], v[248:249], v[246:247]
	v_lshlrev_b32_e32 v248, 16, v65
	v_and_b32_e32 v249, 0xffff0000, v65
	v_pk_fma_f32 v[246:247], v[18:19], v[248:249], v[246:247]
	v_pk_add_f32 v[246:247], v[26:27], v[246:247]
	v_lshlrev_b32_e32 v248, 16, v69
	v_and_b32_e32 v249, 0xffff0000, v69
	v_pk_mul_f32 v[246:247], v[246:247], v[248:249]
	v_cvt_pk_bf16_f32 v199, v246, v247
	v_lshlrev_b32_e32 v246, 16, v62
	v_and_b32_e32 v247, 0xffff0000, v62
	v_pk_mul_f32 v[246:247], v[12:13], v[246:247]
	v_lshlrev_b32_e32 v248, 16, v58
	v_and_b32_e32 v249, 0xffff0000, v58
	v_pk_fma_f32 v[246:247], v[4:5], v[248:249], v[246:247]
	v_lshlrev_b32_e32 v248, 16, v66
	v_and_b32_e32 v249, 0xffff0000, v66
	v_pk_fma_f32 v[246:247], v[20:21], v[248:249], v[246:247]
	v_pk_add_f32 v[246:247], v[28:29], v[246:247]
	v_lshlrev_b32_e32 v248, 16, v70
	v_and_b32_e32 v249, 0xffff0000, v70
	v_pk_mul_f32 v[246:247], v[246:247], v[248:249]
	v_cvt_pk_bf16_f32 v200, v246, v247
	v_lshlrev_b32_e32 v246, 16, v63
	v_and_b32_e32 v247, 0xffff0000, v63
	v_pk_mul_f32 v[246:247], v[14:15], v[246:247]
	v_lshlrev_b32_e32 v248, 16, v59
	v_and_b32_e32 v249, 0xffff0000, v59
	v_pk_fma_f32 v[246:247], v[6:7], v[248:249], v[246:247]
	v_lshlrev_b32_e32 v248, 16, v67
	v_and_b32_e32 v249, 0xffff0000, v67
	v_pk_fma_f32 v[246:247], v[22:23], v[248:249], v[246:247]
	v_pk_add_f32 v[246:247], v[30:31], v[246:247]
	v_lshlrev_b32_e32 v248, 16, v71
	v_and_b32_e32 v249, 0xffff0000, v71
	v_pk_mul_f32 v[246:247], v[246:247], v[248:249]
	v_cvt_pk_bf16_f32 v201, v246, v247
	v_lshl_add_u64 v[64:65], v[144:145], 0, s[34:35]
	s_add_i32 s34, 0, 0x1e400
	v_and_b32_e32 v66, 0xfff, v64
	v_cmp_ne_u32_e64 s[20:21], 0, v66
	v_add_u32_e32 v185, 0, v143
	v_add_u32_e32 v116, 0x1e600, v185
	s_waitcnt lgkmcnt(5)
	v_pk_mul_f32 v[192:193], v[98:99], v[192:193]
	v_pk_mul_f32 v[190:191], v[96:97], v[190:191]
	v_pk_mul_f32 v[98:99], v[102:103], v[192:193]
	v_pk_mul_f32 v[96:97], v[100:101], v[190:191]
	v_cndmask_b32_e64 v56, 0, 1, s[20:21]
	v_cvt_pk_bf16_f32 v100, v96, v97
	v_cvt_pk_bf16_f32 v101, v98, v99
	v_sub_co_u32_e64 v56, s[20:21], v64, v56
	ds_read_b128 v[116:119], v116
	ds_write_b64 v182, v[100:101]
	v_pk_mul_f32 v[100:101], v[104:105], v[190:191]
	v_pk_mul_f32 v[102:103], v[106:107], v[192:193]
	v_subbrev_co_u32_e64 v57, s[20:21], 0, v65, s[20:21]
	v_cvt_pk_bf16_f32 v104, v100, v101
	v_cvt_pk_bf16_f32 v105, v102, v103
	v_cmp_ne_u32_e64 s[20:21], s62, v66
	ds_write_b64 v182, v[104:105] offset:4352
	v_pk_mul_f32 v[104:105], v[108:109], v[190:191]
	v_pk_mul_f32 v[106:107], v[110:111], v[192:193]
	v_cndmask_b32_e64 v66, 0, 1, s[20:21]
	v_mov_b32_e32 v67, s35
	v_cvt_pk_bf16_f32 v108, v104, v105
	v_cvt_pk_bf16_f32 v109, v106, v107
	v_lshlrev_b64 v[68:69], 11, v[64:65]
	v_lshl_add_u64 v[64:65], v[64:65], 0, v[66:67]
	ds_write_b64 v182, v[108:109] offset:8704
	v_pk_mul_f32 v[108:109], v[112:113], v[190:191]
	v_pk_mul_f32 v[110:111], v[114:115], v[192:193]
	v_lshlrev_b64 v[56:57], 11, v[56:57]
	v_lshlrev_b64 v[64:65], 11, v[64:65]
	v_cvt_pk_bf16_f32 v112, v108, v109
	v_cvt_pk_bf16_f32 v113, v110, v111
	v_lshl_add_u64 v[56:57], v[134:135], 0, v[56:57]
	v_lshl_add_u64 v[60:61], v[134:135], 0, v[68:69]
	v_lshl_add_u64 v[64:65], v[134:135], 0, v[64:65]
	v_lshl_add_u64 v[68:69], v[136:137], 0, v[68:69]
	ds_write_b64 v182, v[112:113] offset:13056
	global_load_dwordx4 v[56:59], v[56:57], off
	s_lshl_b32 s48, s48, 6
	global_load_dwordx4 v[60:63], v[60:61], off
	s_nop 0
	global_load_dwordx4 v[64:67], v[64:65], off
	s_nop 0
	global_load_dwordx4 v[68:71], v[68:69], off nt
	s_waitcnt lgkmcnt(0)
	s_barrier
	ds_read_b128 v[218:221], v183
	ds_read_b128 v[230:233], v183 offset:64
	ds_read_b128 v[242:245], v183 offset:128
	global_store_dwordx4 v[152:153], v[198:201], off
	s_nop 1
	s_waitcnt lgkmcnt(2)
	v_mfma_f32_16x16x32_bf16 v[198:201], v[218:221], v[122:125], 0
	v_mfma_f32_16x16x32_bf16 v[202:205], v[218:221], v[126:129], 0
	ds_read_b128 v[218:221], v183 offset:192
	s_waitcnt lgkmcnt(2)
	v_mfma_f32_16x16x32_bf16 v[198:201], v[230:233], v[130:133], v[198:201]
	v_mfma_f32_16x16x32_bf16 v[202:205], v[230:233], v[160:163], v[202:205]
	ds_read_b128 v[230:233], v170 offset:61440
	ds_read_b128 v[122:125], v171 offset:44032
	ds_read_b128 v[126:129], v172 offset:44032
	s_waitcnt lgkmcnt(4)
	v_mfma_f32_16x16x32_bf16 v[198:201], v[242:245], v[210:213], v[198:201]
	v_mfma_f32_16x16x32_bf16 v[202:205], v[242:245], v[154:157], v[202:205]
	ds_read_b128 v[242:245], v170 offset:61504
	ds_read_b128 v[130:133], v171 offset:44096
	ds_read_b128 v[160:163], v172 offset:44096
	s_waitcnt lgkmcnt(6)
	v_mfma_f32_16x16x32_bf16 v[198:201], v[218:221], v[206:209], v[198:201]
	v_mfma_f32_16x16x32_bf16 v[202:205], v[218:221], v[174:177], v[202:205]
	ds_read_b128 v[218:221], v170 offset:61568
	ds_read_b128 v[210:213], v171 offset:44160
	ds_read_b128 v[154:157], v172 offset:44160
	s_waitcnt lgkmcnt(6)
	v_mfma_f32_16x16x32_bf16 v[190:193], v[230:233], v[122:125], 0
	v_mfma_f32_16x16x32_bf16 v[194:197], v[230:233], v[126:129], 0
	ds_read_b128 v[230:233], v170 offset:61632
	ds_read_b128 v[206:209], v171 offset:44224
	ds_read_b128 v[174:177], v172 offset:44224
	s_waitcnt lgkmcnt(6)
	v_mfma_f32_16x16x32_bf16 v[190:193], v[242:245], v[130:133], v[190:193]
	v_mfma_f32_16x16x32_bf16 v[194:197], v[242:245], v[160:163], v[194:197]
	ds_read_b64_tr_b16 v[242:243], v139
	ds_read_b64_tr_b16 v[244:245], v139 offset:512
	ds_read_b128 v[246:249], v142
	ds_read_b128 v[250:253], v159
	s_waitcnt lgkmcnt(7)
	v_mfma_f32_16x16x32_bf16 v[190:193], v[218:221], v[210:213], v[190:193]
	v_mfma_f32_16x16x32_bf16 v[194:197], v[218:221], v[154:157], v[194:197]
	ds_read_b64_tr_b16 v[218:219], v139 offset:4096
	ds_read_b64_tr_b16 v[220:221], v139 offset:4608
	ds_read_b128 v[222:225], v142 offset:64
	ds_read_b128 v[226:229], v159 offset:64
	s_waitcnt lgkmcnt(8)
	v_mfma_f32_16x16x32_bf16 v[190:193], v[230:233], v[206:209], v[190:193]
	v_mfma_f32_16x16x32_bf16 v[194:197], v[230:233], v[174:177], v[194:197]
	s_nop 6
	v_cndmask_b32_e32 v190, 0, v190, vcc
	v_cndmask_b32_e64 v191, 0, v191, s[6:7]
	v_cndmask_b32_e64 v192, 0, v192, s[8:9]
	v_cndmask_b32_e64 v193, 0, v193, s[10:11]
	v_cvt_pk_bf16_f32 v190, v190, v191
	v_cvt_pk_bf16_f32 v191, v192, v193
	v_cndmask_b32_e64 v194, 0, v194, s[12:13]
	v_cndmask_b32_e64 v195, 0, v195, s[14:15]
	v_cndmask_b32_e64 v196, 0, v196, s[16:17]
	v_cndmask_b32_e64 v197, 0, v197, s[18:19]
	v_cvt_pk_bf16_f32 v194, v194, v195
	v_cvt_pk_bf16_f32 v195, v196, v197
	ds_write_b64 v164, v[190:191] offset:9216
	ds_write_b64 v180, v[194:195] offset:9216
	ds_read_b64_tr_b16 v[190:191], v178 offset:17408
	ds_read_b64_tr_b16 v[192:193], v178 offset:18496
	ds_read_b64_tr_b16 v[194:195], v178 offset:26112
	ds_read_b64_tr_b16 v[196:197], v178 offset:27200
	s_waitcnt lgkmcnt(10)
	v_mfma_f32_16x16x32_bf16 v[198:201], v[242:245], v[246:249], v[198:201]
	v_mfma_f32_16x16x32_bf16 v[202:205], v[242:245], v[250:253], v[202:205]
	ds_read_b64_tr_b16 v[242:243], v186
	ds_read_b64_tr_b16 v[244:245], v186 offset:512
	ds_read_b64_tr_b16 v[246:247], v187
	ds_read_b64_tr_b16 v[248:249], v187 offset:512
	s_waitcnt lgkmcnt(10)
	v_mfma_f32_16x16x32_bf16 v[198:201], v[218:221], v[222:225], v[198:201]
	v_mfma_f32_16x16x32_bf16 v[202:205], v[218:221], v[226:229], v[202:205]
	ds_read_b64_tr_b16 v[218:219], v188
	ds_read_b64_tr_b16 v[220:221], v188 offset:512
	ds_read_b64_tr_b16 v[222:223], v189
	ds_read_b64_tr_b16 v[224:225], v189 offset:512
	s_waitcnt lgkmcnt(8)
	ds_read_b64_tr_b16 v[230:231], v186 offset:4096
	ds_read_b64_tr_b16 v[232:233], v186 offset:4608
	ds_read_b64_tr_b16 v[234:235], v187 offset:4096
	ds_read_b64_tr_b16 v[236:237], v187 offset:4608
	s_waitcnt lgkmcnt(8)
	v_mfma_f32_16x16x32_bf16 v[96:99], v[190:193], v[242:245], v[96:99]
	v_mfma_f32_16x16x32_bf16 v[100:103], v[190:193], v[246:249], v[100:103]
	ds_read_b64_tr_b16 v[242:243], v188 offset:4096
	ds_read_b64_tr_b16 v[244:245], v188 offset:4608
	ds_read_b64_tr_b16 v[246:247], v189 offset:4096
	ds_read_b64_tr_b16 v[248:249], v189 offset:4608
	v_cvt_pk_bf16_f32 v198, v198, v199
	v_cvt_pk_bf16_f32 v199, v200, v201
	v_cvt_pk_bf16_f32 v200, v202, v203
	v_cvt_pk_bf16_f32 v201, v204, v205
	v_add_u32_e32 v254, s48, v173
	v_mad_u64_u32 v[254:255], s[20:21], v254, s42, 0
	v_lshl_add_u64 v[254:255], v[254:255], 1, v[150:151]
	v_permlane16_swap_b32_e32 v198, v200
	v_permlane16_swap_b32_e32 v199, v201
	global_store_dwordx4 v[254:255], v[198:201], off
	s_waitcnt lgkmcnt(8)
	v_mfma_f32_16x16x32_bf16 v[104:107], v[190:193], v[218:221], v[104:107]
	v_mfma_f32_16x16x32_bf16 v[214:217], v[190:193], v[222:225], v[108:111]
	s_waitcnt lgkmcnt(4)
	v_mfma_f32_16x16x32_bf16 v[112:115], v[194:197], v[230:233], v[96:99]
	v_mfma_f32_16x16x32_bf16 v[108:111], v[194:197], v[234:237], v[100:103]
	s_waitcnt lgkmcnt(0)
	v_mfma_f32_16x16x32_bf16 v[104:107], v[194:197], v[242:245], v[104:107]
	v_mfma_f32_16x16x32_bf16 v[100:103], v[194:197], v[246:249], v[214:217]
	s_min_u32 s20, s44, 59
	s_waitcnt lgkmcnt(0)
	s_barrier
	v_add_u32_e32 v96, s61, v143
	ds_read_b128 v[222:225], v96
	s_waitcnt vmcnt(18)
	ds_write_b128 v168, v[72:75]
	s_waitcnt vmcnt(17)
	ds_write_b128 v168, v[80:83] offset:8704
	s_waitcnt vmcnt(15)
	ds_write_b128 v168, v[76:79] offset:17408
	s_waitcnt vmcnt(14)
	ds_write_b128 v168, v[84:87] offset:26112
	s_waitcnt vmcnt(16)
	ds_write_b128 v169, v[88:91] offset:34816
	v_add_u32_e32 v72, s34, v138
	s_add_i32 s34, s20, 4
	s_waitcnt vmcnt(13)
	s_cmp_lg_u32 s69, 0
	s_cbranch_scc1 .Lev_skip_b
	ds_write_b128 v72, v[92:95]
